# phase-0 to phase-1 boundary uses the XCD-hierarchical grid barrier (as all other boundaries) instead of the cooperative-groups grid sync
# baseline (speedup 1.0000x reference)
; __device__ __forceinline__ void xcd_barrier(const XcdBarrier& b) {
;     asm volatile("s_waitcnt vmcnt(0)" ::: "memory");
;     __syncthreads();
;     if (threadIdx.x == 0) {
;         unsigned* bar = b.bar;
;         __builtin_amdgcn_s_waitcnt(0);
;         unsigned nloc = b.st[0], nx = b.st[1];
;         if (nloc == 0u) { xcd_barrier_complete(bar, b.x, nloc, nx); b.st[0] = nloc; b.st[1] = nx; }
; __global__ void __launch_bounds__(NWAVES * 64, 2) fwd_kernel(Args a) {
;     ...
;         if (ph + 1 < a.ph_hi) { if (ph == 0) cg::this_grid().sync(); else xcd_barrier(xbar); }
.LBB0_793:
	s_add_i32 s64, s64, 1
	s_cmp_ge_i32 s64, s65
	s_mov_b64 s[0:1], -1
	s_cbranch_scc1 .LBB0_10
	v_readlane_b32 s0, v254, 55
	v_readlane_b32 s1, v254, 56
	s_and_b64 vcc, exec, s[0:1]
	s_waitcnt vmcnt(0)
	s_waitcnt vmcnt(0) lgkmcnt(0)
	s_barrier
	s_mov_b64 s[0:1], exec
	v_readlane_b32 s2, v252, 3
	v_readlane_b32 s3, v252, 4
	s_and_b64 s[2:3], s[0:1], s[2:3]
	s_mov_b64 exec, s[2:3]
	s_cbranch_execz .LBB0_849
	v_readlane_b32 s2, v254, 28
	s_waitcnt vmcnt(0) expcnt(0) lgkmcnt(0)
	s_nop 0
	v_mov_b32_e32 v0, s2
	ds_read_b32 v3, v0
	v_readlane_b32 s2, v254, 29
	s_waitcnt lgkmcnt(0)
	v_cmp_ne_u32_e32 vcc, 0, v3
	v_mov_b32_e32 v0, s2
	ds_read_b32 v0, v0
	s_cbranch_vccnz .LBB0_813
	v_readlane_b32 s4, v252, 5
	v_readlane_b32 s5, v252, 6
	s_load_dwordx2 s[2:3], s[4:5], 0x4
	v_readlane_b32 s4, v254, 27
	s_mov_b32 s9, 1
	s_waitcnt lgkmcnt(0)
	s_mul_i32 s8, s2, s4
	s_mul_i32 s8, s8, s3
	s_branch .LBB0_799
